# gate pre-activation task: XN row loads with the nt hint (stream should not displace GEMM weight tiles in L2), on top of v73
# baseline (speedup 1.0000x reference)
; __device__ __forceinline__ f32x4 mfma16(bf16x8 a, bf16x8 b, f32x4 c) { return __builtin_amdgcn_mfma_f32_16x16x32_bf16(a, b, c, 0, 0, 0); }
; __device__ __forceinline__ void gate_tile(const Params& P, int tile, int lane) {
;     ...
;     const bf16* ap = (const bf16*)(P.ws + WS_XN) + (size_t)(16 * tile + l15) * 1024 + 8 * q4;
;     const bf16* bp = (const bf16*)(P.ws + WS_WAB) + (size_t)l15 * 1024 + 8 * q4;
;     f32x4 acc = {0.f, 0.f, 0.f, 0.f};
; #pragma unroll 16
;     for (int ks = 0; ks < 32; ++ks) acc = mfma16(*(const bf16x8*)(ap + 32 * ks), *(const bf16x8*)(bp + 32 * ks), acc);
;     float* Gd = (float*)(P.ws + WS_G); float* Bd = (float*)(P.ws + WS_BETA);
;     const int c = l15;
;     const float al = (c < 8) ? -expf(P.a_log[c]) : 0.f, db = (c < 8) ? P.dt_bias[c] : 0.f;
.LBB0_148:
	v_lshl_add_u64 v[24:25], v[22:23], 0, s[52:53]
	s_waitcnt vmcnt(0)
	v_add_co_u32_e32 v26, vcc, 0x23900000, v24
	s_nop 1
	v_addc_co_u32_e32 v27, vcc, 0, v25, vcc
	v_lshl_add_u64 v[24:25], v[20:21], 0, s[52:53]
	v_add_co_u32_e32 v24, vcc, 0xdc0000, v24
	s_add_u32 s52, s52, 0x400
	s_nop 0
	v_addc_co_u32_e32 v25, vcc, 0, v25, vcc
	s_addc_u32 s53, s53, 0
	s_cmpk_eq_i32 s52, 0x800
	global_load_dwordx4 v[28:31], v[24:25], off
	global_load_dwordx4 v[32:35], v[24:25], off offset:64
	global_load_dwordx4 v[36:39], v[24:25], off offset:128
	global_load_dwordx4 v[44:47], v[24:25], off offset:192
	global_load_dwordx4 v[48:51], v[24:25], off offset:256
	global_load_dwordx4 v[52:55], v[24:25], off offset:320
	global_load_dwordx4 v[56:59], v[24:25], off offset:384
	global_load_dwordx4 v[60:63], v[24:25], off offset:448
	global_load_dwordx4 v[66:69], v[26:27], off nt
	global_load_dwordx4 v[70:73], v[26:27], off offset:64 nt
	global_load_dwordx4 v[74:77], v[26:27], off offset:128 nt
	global_load_dwordx4 v[78:81], v[26:27], off offset:192 nt
	global_load_dwordx4 v[82:85], v[26:27], off offset:256 nt
	global_load_dwordx4 v[86:89], v[26:27], off offset:320 nt
	global_load_dwordx4 v[90:93], v[26:27], off offset:384 nt
	global_load_dwordx4 v[94:97], v[26:27], off offset:448 nt
	global_load_dwordx4 v[98:101], v[26:27], off offset:512 nt
	global_load_dwordx4 v[102:105], v[26:27], off offset:576 nt
	global_load_dwordx4 v[106:109], v[26:27], off offset:640 nt
	global_load_dwordx4 v[110:113], v[26:27], off offset:704 nt
	global_load_dwordx4 v[114:117], v[26:27], off offset:768 nt
	global_load_dwordx4 v[118:121], v[26:27], off offset:832 nt
	global_load_dwordx4 v[122:125], v[26:27], off offset:896 nt
	global_load_dwordx4 v[126:129], v[26:27], off offset:960 nt
	s_waitcnt vmcnt(15)
	v_mfma_f32_16x16x32_bf16 v[2:5], v[66:69], v[28:31], v[2:5]
	global_load_dwordx4 v[28:31], v[24:25], off offset:512
	s_waitcnt vmcnt(15)
	v_mfma_f32_16x16x32_bf16 v[2:5], v[70:73], v[32:35], v[2:5]
	global_load_dwordx4 v[32:35], v[24:25], off offset:576
	s_waitcnt vmcnt(15)
	v_mfma_f32_16x16x32_bf16 v[2:5], v[74:77], v[36:39], v[2:5]
	global_load_dwordx4 v[36:39], v[24:25], off offset:640
	s_waitcnt vmcnt(15)
	v_mfma_f32_16x16x32_bf16 v[2:5], v[78:81], v[44:47], v[2:5]
	global_load_dwordx4 v[44:47], v[24:25], off offset:704
	s_waitcnt vmcnt(15)
	v_mfma_f32_16x16x32_bf16 v[2:5], v[82:85], v[48:51], v[2:5]
	global_load_dwordx4 v[48:51], v[24:25], off offset:768
	s_waitcnt vmcnt(15)
	v_mfma_f32_16x16x32_bf16 v[2:5], v[86:89], v[52:55], v[2:5]
	global_load_dwordx4 v[52:55], v[24:25], off offset:832
	s_waitcnt vmcnt(15)
	v_mfma_f32_16x16x32_bf16 v[2:5], v[90:93], v[56:59], v[2:5]
	global_load_dwordx4 v[56:59], v[24:25], off offset:896
	s_waitcnt vmcnt(15)
	v_mfma_f32_16x16x32_bf16 v[2:5], v[94:97], v[60:63], v[2:5]
	global_load_dwordx4 v[60:63], v[24:25], off offset:960
	s_waitcnt vmcnt(7)
	v_mfma_f32_16x16x32_bf16 v[2:5], v[98:101], v[28:31], v[2:5]
	s_waitcnt vmcnt(6)
	v_mfma_f32_16x16x32_bf16 v[2:5], v[102:105], v[32:35], v[2:5]
	s_waitcnt vmcnt(5)
	v_mfma_f32_16x16x32_bf16 v[2:5], v[106:109], v[36:39], v[2:5]
	s_waitcnt vmcnt(4)
	v_mfma_f32_16x16x32_bf16 v[2:5], v[110:113], v[44:47], v[2:5]
	s_waitcnt vmcnt(3)
	v_mfma_f32_16x16x32_bf16 v[2:5], v[114:117], v[48:51], v[2:5]
	s_waitcnt vmcnt(2)
	v_mfma_f32_16x16x32_bf16 v[2:5], v[118:121], v[52:55], v[2:5]
	s_waitcnt vmcnt(1)
	v_mfma_f32_16x16x32_bf16 v[2:5], v[122:125], v[56:59], v[2:5]
	s_waitcnt vmcnt(0)
	v_mfma_f32_16x16x32_bf16 v[2:5], v[126:129], v[60:63], v[2:5]
	s_cbranch_scc0 .LBB0_148
	v_mov_b32_e32 v26, 0
	v_mov_b32_e32 v19, 0
	s_and_saveexec_b64 s[52:53], s[0:1]
	s_cbranch_execz .LBB0_151
	global_load_dword v19, v[6:7], off
	s_waitcnt vmcnt(0)
	v_mul_f32_e32 v22, 0x3fb8aa3b, v19
	v_rndne_f32_e32 v23, v22
	v_fma_f32 v24, v19, s40, -v22
	v_sub_f32_e32 v22, v22, v23
	v_fmac_f32_e32 v24, 0x32a5705f, v19
	v_add_f32_e32 v22, v22, v24
	v_cvt_i32_f32_e32 v23, v23
	v_exp_f32_e32 v22, v22
	v_cmp_ngt_f32_e32 vcc, s97, v19
	v_ldexp_f32 v22, v22, v23
	s_nop 0
	v_cndmask_b32_e32 v22, 0, v22, vcc
	v_cmp_nlt_f32_e32 vcc, s35, v19
	s_nop 1
	v_cndmask_b32_e32 v19, v154, v22, vcc
	v_xor_b32_e32 v19, 0x80000000, v19
